# attention: the O-rescale test at the head of the MFMA segment is a scalar flag set by the lazy-rescale path (was v_cmp -> vcc -> branch)
# baseline (speedup 1.0000x reference)
; __device__ __forceinline__ float fexp2(float x) { return __builtin_amdgcn_exp2f(x); }
; __device__ __forceinline__ float max3f(float a, float b, float c) { float r; asm("v_max3_f32 %0, %1, %2, %3" : "=v"(r) : "v"(a), "v"(b), "v"(c)); return r; }
; __device__ __forceinline__ void attn_phase(LAS unsigned char* lds, const bf16_t* Q, const bf16_t* Kimg, const bf16_t* Vimg, const bf16_t* Kmeta, const bf16_t* Vmeta,
;                                            bf16_t* O, const float* lamp, const float* sublnw, float lambda_init, int G) {
;     ...
;                     float mxa = max3f(sA[0], sA[1], sA[2]), mxb = max3f(sB[0], sB[1], sB[2]);
; #pragma unroll
;                     for (int r = 3; r < 15; r += 2) { mxa = max3f(mxa, sA[r], sA[r + 1]); mxb = max3f(mxb, sB[r], sB[r + 1]); }
;                     float mx = max3f(mxa, mxb, sA[15]); mx = fmaxf(mx, sB[15]);
;                     mx = half_max(mx);
;                     alpha = 1.f;
;                     if (__any(mx > 64.f)) { const float d = fmaxf(mx, 0.f); alpha = fexp2(-d); mrun += d;
; #pragma unroll
;                         for (int r = 0; r < 16; ++r) { sA[r] -= d; sB[r] -= d; } }
.LBB0_758:
	s_add_i32 s10, s38, 0x4000
	s_and_b32 s10, s10, 0xc000
	v_add_u32_e32 v234, s10, v220
	ds_read_b128 v[184:187], v234
	ds_read_b128 v[188:191], v234 offset:512
	ds_read_b128 v[202:205], v234 offset:1024
	ds_read_b128 v[246:249], v234 offset:1536
	v_max3_f32 v2, v18, v19, v20
	v_max3_f32 v3, v34, v35, v36
	v_max3_f32 v2, v2, v21, v22
	v_max3_f32 v3, v3, v37, v38
	v_max3_f32 v2, v2, v23, v24
	v_max3_f32 v3, v3, v39, v40
	v_max3_f32 v2, v2, v25, v26
	v_max3_f32 v3, v3, v41, v42
	v_max3_f32 v2, v2, v27, v28
	v_max3_f32 v3, v3, v43, v44
	v_max3_f32 v2, v2, v29, v30
	v_max3_f32 v3, v3, v45, v46
	v_max3_f32 v2, v2, v31, v32
	v_max3_f32 v3, v3, v47, v48
	v_max3_f32 v2, v2, v3, v33
	v_max_f32_e32 v2, v2, v49
	v_mov_b32_e32 v3, v2
	s_nop 1
	v_permlane32_swap_b32_e32 v2, v3
	v_max_f32_e32 v2, v2, v3
	v_cmp_lt_f32_e32 vcc, s45, v2
	s_cbranch_vccz .LBB0_760
	v_max_f32_e32 v2, v2, v2
	v_max_f32_e32 v2, 0, v2
	v_exp_f32_e64 v178, -v2
	s_mov_b32 s98, 1
	v_pk_add_f32 v[18:19], v[18:19], v[2:3] op_sel_hi:[1,0] neg_lo:[0,1] neg_hi:[0,1]
	v_pk_add_f32 v[34:35], v[34:35], v[2:3] op_sel_hi:[1,0] neg_lo:[0,1] neg_hi:[0,1]
	v_pk_add_f32 v[20:21], v[20:21], v[2:3] op_sel_hi:[1,0] neg_lo:[0,1] neg_hi:[0,1]
	v_pk_add_f32 v[36:37], v[36:37], v[2:3] op_sel_hi:[1,0] neg_lo:[0,1] neg_hi:[0,1]
	v_pk_add_f32 v[22:23], v[22:23], v[2:3] op_sel_hi:[1,0] neg_lo:[0,1] neg_hi:[0,1]
	v_pk_add_f32 v[38:39], v[38:39], v[2:3] op_sel_hi:[1,0] neg_lo:[0,1] neg_hi:[0,1]
	v_pk_add_f32 v[24:25], v[24:25], v[2:3] op_sel_hi:[1,0] neg_lo:[0,1] neg_hi:[0,1]
	v_pk_add_f32 v[40:41], v[40:41], v[2:3] op_sel_hi:[1,0] neg_lo:[0,1] neg_hi:[0,1]
	v_pk_add_f32 v[26:27], v[26:27], v[2:3] op_sel_hi:[1,0] neg_lo:[0,1] neg_hi:[0,1]
	v_pk_add_f32 v[42:43], v[42:43], v[2:3] op_sel_hi:[1,0] neg_lo:[0,1] neg_hi:[0,1]
	v_pk_add_f32 v[28:29], v[28:29], v[2:3] op_sel_hi:[1,0] neg_lo:[0,1] neg_hi:[0,1]
	v_pk_add_f32 v[44:45], v[44:45], v[2:3] op_sel_hi:[1,0] neg_lo:[0,1] neg_hi:[0,1]
	v_pk_add_f32 v[30:31], v[30:31], v[2:3] op_sel_hi:[1,0] neg_lo:[0,1] neg_hi:[0,1]
	v_pk_add_f32 v[46:47], v[46:47], v[2:3] op_sel_hi:[1,0] neg_lo:[0,1] neg_hi:[0,1]
	v_pk_add_f32 v[32:33], v[32:33], v[2:3] op_sel_hi:[1,0] neg_lo:[0,1] neg_hi:[0,1]
	v_pk_add_f32 v[48:49], v[48:49], v[2:3] op_sel_hi:[1,0] neg_lo:[0,1] neg_hi:[0,1]
	v_add_f32_e32 v173, v173, v2
	s_branch .LBB0_761
.LBB0_760:
	v_mov_b32_e32 v178, 1.0
	s_mov_b32 s98, 0

; #define VFR(F, s4) _Pragma("unroll") for (int i = 0; i < 4; ++i) F[i] = *(const LAS bf16x8*)(Vb + (2 * (s4) + hi) * 2048 + (32 * i + l31) * 16)
; __device__ __forceinline__ void attn_phase(LAS unsigned char* lds, const bf16_t* Q, const bf16_t* Kimg, const bf16_t* Vimg, const bf16_t* Kmeta, const bf16_t* Vmeta,
;                                            bf16_t* O, const float* lamp, const float* sublnw, float lambda_init, int G) {
;     ...
;                     __builtin_amdgcn_s_setprio(1);
;                     VFR(fa, 0);
;                     if (__any(alpha != 1.f)) {
; #pragma unroll
;                         for (int d = 0; d < 4; ++d)
; #pragma unroll
;                             for (int r = 0; r < 16; ++r) o[d][r] *= alpha;
;                     }
.LBB0_766:
	s_and_b64 vcc, exec, s[30:31]
	s_cbranch_vccnz .LBB0_770
	s_setprio 1
	s_cmp_eq_u32 s98, 0
	s_cbranch_scc1 .Latt_noalpha
	v_pk_mul_f32 v[112:113], v[112:113], v[178:179] op_sel_hi:[1,0]
	v_pk_mul_f32 v[110:111], v[110:111], v[178:179] op_sel_hi:[1,0]
	v_pk_mul_f32 v[108:109], v[108:109], v[178:179] op_sel_hi:[1,0]
	v_pk_mul_f32 v[106:107], v[106:107], v[178:179] op_sel_hi:[1,0]
	v_pk_mul_f32 v[104:105], v[104:105], v[178:179] op_sel_hi:[1,0]
	v_pk_mul_f32 v[102:103], v[102:103], v[178:179] op_sel_hi:[1,0]
	v_pk_mul_f32 v[100:101], v[100:101], v[178:179] op_sel_hi:[1,0]
	v_pk_mul_f32 v[98:99], v[98:99], v[178:179] op_sel_hi:[1,0]
	v_pk_mul_f32 v[96:97], v[96:97], v[178:179] op_sel_hi:[1,0]
	v_pk_mul_f32 v[94:95], v[94:95], v[178:179] op_sel_hi:[1,0]
	v_pk_mul_f32 v[92:93], v[92:93], v[178:179] op_sel_hi:[1,0]
	v_pk_mul_f32 v[90:91], v[90:91], v[178:179] op_sel_hi:[1,0]
	v_pk_mul_f32 v[88:89], v[88:89], v[178:179] op_sel_hi:[1,0]
	v_pk_mul_f32 v[86:87], v[86:87], v[178:179] op_sel_hi:[1,0]
	v_pk_mul_f32 v[84:85], v[84:85], v[178:179] op_sel_hi:[1,0]
	v_pk_mul_f32 v[82:83], v[82:83], v[178:179] op_sel_hi:[1,0]
	v_pk_mul_f32 v[80:81], v[80:81], v[178:179] op_sel_hi:[1,0]
	v_pk_mul_f32 v[78:79], v[78:79], v[178:179] op_sel_hi:[1,0]
	v_pk_mul_f32 v[76:77], v[76:77], v[178:179] op_sel_hi:[1,0]
	v_pk_mul_f32 v[74:75], v[74:75], v[178:179] op_sel_hi:[1,0]
	v_pk_mul_f32 v[72:73], v[72:73], v[178:179] op_sel_hi:[1,0]
	v_pk_mul_f32 v[70:71], v[70:71], v[178:179] op_sel_hi:[1,0]
	v_pk_mul_f32 v[68:69], v[68:69], v[178:179] op_sel_hi:[1,0]
	v_pk_mul_f32 v[66:67], v[66:67], v[178:179] op_sel_hi:[1,0]
	v_pk_mul_f32 v[64:65], v[64:65], v[178:179] op_sel_hi:[1,0]
	v_pk_mul_f32 v[62:63], v[62:63], v[178:179] op_sel_hi:[1,0]
	v_pk_mul_f32 v[60:61], v[60:61], v[178:179] op_sel_hi:[1,0]
	v_pk_mul_f32 v[58:59], v[58:59], v[178:179] op_sel_hi:[1,0]
	v_pk_mul_f32 v[56:57], v[56:57], v[178:179] op_sel_hi:[1,0]
	v_pk_mul_f32 v[54:55], v[54:55], v[178:179] op_sel_hi:[1,0]
	v_pk_mul_f32 v[52:53], v[52:53], v[178:179] op_sel_hi:[1,0]
	v_pk_mul_f32 v[50:51], v[50:51], v[178:179] op_sel_hi:[1,0]
